# SwiGLU epilogue of both FFN-in GEMMs rewritten with packed f32 ops on register pairs, four pairs interleaved per row (same math, no s_nop), on top of gate epilogue
# baseline (speedup 1.0000x reference)
.LBB0_143:
	s_add_u32 s22, s20, 0xfff80080
	s_addc_u32 s23, s21, -1
	s_add_i32 s44, 0, 0x10000
	v_add_u32_e32 v156, s44, v141
	ds_read_b128 v[144:147], v156
	ds_read_b128 v[148:151], v156 offset:1024
	ds_read_b128 v[152:155], v156 offset:2048
	ds_read_b128 v[156:159], v156 offset:3072
	s_cmp_eq_u32 s43, 28
	s_cselect_b32 s25, s13, s23
	s_cselect_b32 s24, s39, s22
	s_cselect_b32 s23, s11, s42
	s_cselect_b32 s22, s40, s41
	v_lshl_add_u64 v[160:161], s[20:21], 0, v[136:137]
	s_add_i32 m0, s19, 0xc000
	ds_read_b128 v[176:179], v143
	ds_read_b128 v[180:183], v143 offset:1024
	ds_read_b128 v[184:187], v143 offset:2048
	ds_read_b128 v[188:191], v143 offset:3072
	ds_read_b128 v[192:195], v143 offset:4096
	ds_read_b128 v[208:211], v143 offset:5120
	ds_read_b128 v[212:215], v143 offset:6144
	ds_read_b128 v[216:219], v143 offset:7168
	global_load_lds_dwordx4 v[160:161], off
	v_lshl_add_u64 v[160:161], s[20:21], 0, v[138:139]
	s_add_i32 m0, s19, 0xe000
	s_nop 0
	global_load_lds_dwordx4 v[160:161], off
	s_waitcnt lgkmcnt(8)
	s_barrier
	s_waitcnt lgkmcnt(0)
	s_setprio 1
	s_waitcnt lgkmcnt(0)
	v_mfma_f32_16x16x32_bf16 v[124:127], v[144:147], v[176:179], v[124:127]
	v_mfma_f32_16x16x32_bf16 v[116:119], v[152:155], v[176:179], v[116:119]
	v_mfma_f32_16x16x32_bf16 v[108:111], v[144:147], v[184:187], v[108:111]
	v_mfma_f32_16x16x32_bf16 v[100:103], v[152:155], v[184:187], v[100:103]
	v_mfma_f32_16x16x32_bf16 v[92:95], v[144:147], v[192:195], v[92:95]
	v_mfma_f32_16x16x32_bf16 v[84:87], v[152:155], v[192:195], v[84:87]
	v_mfma_f32_16x16x32_bf16 v[76:79], v[144:147], v[212:215], v[76:79]
	v_mfma_f32_16x16x32_bf16 v[68:71], v[152:155], v[212:215], v[68:71]
	v_mfma_f32_16x16x32_bf16 v[124:127], v[148:151], v[180:183], v[124:127]
	v_mfma_f32_16x16x32_bf16 v[116:119], v[156:159], v[180:183], v[116:119]
	v_mfma_f32_16x16x32_bf16 v[108:111], v[148:151], v[188:191], v[108:111]
	v_mfma_f32_16x16x32_bf16 v[100:103], v[156:159], v[188:191], v[100:103]
	v_mfma_f32_16x16x32_bf16 v[92:95], v[148:151], v[208:211], v[92:95]
	v_mfma_f32_16x16x32_bf16 v[84:87], v[156:159], v[208:211], v[84:87]
	v_mfma_f32_16x16x32_bf16 v[76:79], v[148:151], v[216:219], v[76:79]
	v_mfma_f32_16x16x32_bf16 v[68:71], v[156:159], v[216:219], v[68:71]
	s_setprio 0
	s_barrier
	s_add_i32 s46, 0, 0x14000
	v_add_u32_e32 v160, s46, v141
	s_add_i32 s44, s44, s28
	ds_read_b128 v[220:223], v160
	ds_read_b128 v[224:227], v160 offset:1024
	ds_read_b128 v[228:231], v160 offset:2048
	ds_read_b128 v[232:235], v160 offset:3072
	v_lshl_add_u64 v[160:161], s[22:23], 0, v[128:129]
	s_mov_b32 m0, s44
	v_lshl_add_u64 v[236:237], s[22:23], 0, v[130:131]
	global_load_lds_dwordx4 v[160:161], off
	s_add_i32 m0, s44, 0x2000
	s_nop 0
	global_load_lds_dwordx4 v[236:237], off
	s_barrier
	s_waitcnt lgkmcnt(0)
	s_setprio 1
	s_waitcnt lgkmcnt(0)
	v_mfma_f32_16x16x32_bf16 v[120:123], v[220:223], v[176:179], v[120:123]
	v_mfma_f32_16x16x32_bf16 v[112:115], v[228:231], v[176:179], v[112:115]
	v_mfma_f32_16x16x32_bf16 v[104:107], v[220:223], v[184:187], v[104:107]
	v_mfma_f32_16x16x32_bf16 v[96:99], v[228:231], v[184:187], v[96:99]
	v_mfma_f32_16x16x32_bf16 v[88:91], v[220:223], v[192:195], v[88:91]
	v_mfma_f32_16x16x32_bf16 v[80:83], v[228:231], v[192:195], v[80:83]
	v_mfma_f32_16x16x32_bf16 v[72:75], v[220:223], v[212:215], v[72:75]
	v_mfma_f32_16x16x32_bf16 v[64:67], v[228:231], v[212:215], v[64:67]
	v_mfma_f32_16x16x32_bf16 v[120:123], v[224:227], v[180:183], v[120:123]
	v_mfma_f32_16x16x32_bf16 v[112:115], v[232:235], v[180:183], v[112:115]
	v_mfma_f32_16x16x32_bf16 v[104:107], v[224:227], v[188:191], v[104:107]
	v_mfma_f32_16x16x32_bf16 v[96:99], v[232:235], v[188:191], v[96:99]
	v_mfma_f32_16x16x32_bf16 v[88:91], v[224:227], v[208:211], v[88:91]
	v_mfma_f32_16x16x32_bf16 v[80:83], v[232:235], v[208:211], v[80:83]
	v_mfma_f32_16x16x32_bf16 v[72:75], v[224:227], v[216:219], v[72:75]
	v_mfma_f32_16x16x32_bf16 v[64:67], v[232:235], v[216:219], v[64:67]
	s_setprio 0
	s_mov_b32 m0, s19
	v_lshl_add_u64 v[238:239], s[24:25], 0, v[134:135]
	s_barrier
	ds_read_b128 v[176:179], v143 offset:16384
	ds_read_b128 v[180:183], v143 offset:17408
	ds_read_b128 v[184:187], v143 offset:18432
	ds_read_b128 v[188:191], v143 offset:19456
	ds_read_b128 v[192:195], v143 offset:20480
	ds_read_b128 v[208:211], v143 offset:21504
	ds_read_b128 v[212:215], v143 offset:22528
	ds_read_b128 v[216:219], v143 offset:23552
	global_load_lds_dwordx4 v[238:239], off
	v_lshl_add_u64 v[240:241], s[24:25], 0, v[132:133]
	s_mov_b32 m0, s30
	s_nop 0
	global_load_lds_dwordx4 v[240:241], off
	s_barrier
	s_waitcnt lgkmcnt(0)
	s_setprio 1
	s_waitcnt lgkmcnt(0)
	v_mfma_f32_16x16x32_bf16 v[60:63], v[144:147], v[176:179], v[60:63]
	v_mfma_f32_16x16x32_bf16 v[52:55], v[152:155], v[176:179], v[52:55]
	v_mfma_f32_16x16x32_bf16 v[44:47], v[144:147], v[184:187], v[44:47]
	v_mfma_f32_16x16x32_bf16 v[36:39], v[152:155], v[184:187], v[36:39]
	v_mfma_f32_16x16x32_bf16 v[28:31], v[144:147], v[192:195], v[28:31]
	v_mfma_f32_16x16x32_bf16 v[20:23], v[152:155], v[192:195], v[20:23]
	v_mfma_f32_16x16x32_bf16 v[12:15], v[144:147], v[212:215], v[12:15]
	v_mfma_f32_16x16x32_bf16 v[4:7], v[152:155], v[212:215], v[4:7]
	v_mfma_f32_16x16x32_bf16 v[60:63], v[148:151], v[180:183], v[60:63]
	v_mfma_f32_16x16x32_bf16 v[52:55], v[156:159], v[180:183], v[52:55]
	v_mfma_f32_16x16x32_bf16 v[44:47], v[148:151], v[188:191], v[44:47]
	v_mfma_f32_16x16x32_bf16 v[36:39], v[156:159], v[188:191], v[36:39]
	v_mfma_f32_16x16x32_bf16 v[28:31], v[148:151], v[208:211], v[28:31]
	v_mfma_f32_16x16x32_bf16 v[20:23], v[156:159], v[208:211], v[20:23]
	v_mfma_f32_16x16x32_bf16 v[12:15], v[148:151], v[216:219], v[12:15]
	v_mfma_f32_16x16x32_bf16 v[4:7], v[156:159], v[216:219], v[4:7]
	s_setprio 0
	s_barrier
	s_add_u32 s44, s22, 0x80000
	s_addc_u32 s45, s23, 0
	s_add_i32 s46, s46, s28
	v_lshl_add_u64 v[144:145], s[44:45], 0, v[128:129]
	s_mov_b32 m0, s46
	s_nop 0
	global_load_lds_dwordx4 v[144:145], off
	v_lshl_add_u64 v[144:145], s[44:45], 0, v[130:131]
	s_add_i32 m0, s46, 0x2000
	s_nop 0
	global_load_lds_dwordx4 v[144:145], off
	s_waitcnt vmcnt(6)
	s_barrier
	s_setprio 1
	v_mfma_f32_16x16x32_bf16 v[56:59], v[220:223], v[176:179], v[56:59]
	v_mfma_f32_16x16x32_bf16 v[48:51], v[228:231], v[176:179], v[48:51]
	v_mfma_f32_16x16x32_bf16 v[40:43], v[220:223], v[184:187], v[40:43]
	v_mfma_f32_16x16x32_bf16 v[32:35], v[228:231], v[184:187], v[32:35]
	v_mfma_f32_16x16x32_bf16 v[24:27], v[220:223], v[192:195], v[24:27]
	v_mfma_f32_16x16x32_bf16 v[16:19], v[228:231], v[192:195], v[16:19]
	v_mfma_f32_16x16x32_bf16 v[8:11], v[220:223], v[212:215], v[8:11]
	v_mfma_f32_16x16x32_bf16 v[0:3], v[228:231], v[212:215], v[0:3]
	v_mfma_f32_16x16x32_bf16 v[56:59], v[224:227], v[180:183], v[56:59]
	v_mfma_f32_16x16x32_bf16 v[48:51], v[232:235], v[180:183], v[48:51]
	v_mfma_f32_16x16x32_bf16 v[40:43], v[224:227], v[188:191], v[40:43]
	v_mfma_f32_16x16x32_bf16 v[32:35], v[232:235], v[188:191], v[32:35]
	v_mfma_f32_16x16x32_bf16 v[24:27], v[224:227], v[208:211], v[24:27]
	v_mfma_f32_16x16x32_bf16 v[16:19], v[232:235], v[208:211], v[16:19]
	v_mfma_f32_16x16x32_bf16 v[8:11], v[224:227], v[216:219], v[8:11]
	v_mfma_f32_16x16x32_bf16 v[0:3], v[232:235], v[216:219], v[0:3]
	s_setprio 0
	s_add_i32 s44, 0, 0x18000
	v_add_u32_e32 v156, s44, v141
	s_barrier
	ds_read_b128 v[144:147], v156
	ds_read_b128 v[148:151], v156 offset:1024
	ds_read_b128 v[152:155], v156 offset:2048
	ds_read_b128 v[156:159], v156 offset:3072
	s_add_u32 s24, s24, 0x80000
	s_addc_u32 s25, s25, 0
	s_mov_b32 m0, s31
	v_lshl_add_u64 v[220:221], s[24:25], 0, v[134:135]
	ds_read_b128 v[176:179], v143 offset:32768
	ds_read_b128 v[180:183], v143 offset:33792
	ds_read_b128 v[184:187], v143 offset:34816
	ds_read_b128 v[188:191], v143 offset:35840
	ds_read_b128 v[192:195], v143 offset:36864
	ds_read_b128 v[208:211], v143 offset:37888
	ds_read_b128 v[212:215], v143 offset:38912
	ds_read_b128 v[216:219], v143 offset:39936
	global_load_lds_dwordx4 v[220:221], off
	v_lshl_add_u64 v[220:221], s[24:25], 0, v[132:133]
	s_mov_b32 m0, s34
	s_nop 0
	global_load_lds_dwordx4 v[220:221], off
	s_waitcnt lgkmcnt(8)
	s_barrier
	s_waitcnt lgkmcnt(0)
	s_setprio 1
	s_waitcnt lgkmcnt(0)
	v_mfma_f32_16x16x32_bf16 v[124:127], v[144:147], v[176:179], v[124:127]
	v_mfma_f32_16x16x32_bf16 v[116:119], v[152:155], v[176:179], v[116:119]
	v_mfma_f32_16x16x32_bf16 v[108:111], v[144:147], v[184:187], v[108:111]
	v_mfma_f32_16x16x32_bf16 v[100:103], v[152:155], v[184:187], v[100:103]
	v_mfma_f32_16x16x32_bf16 v[92:95], v[144:147], v[192:195], v[92:95]
	v_mfma_f32_16x16x32_bf16 v[84:87], v[152:155], v[192:195], v[84:87]
	v_mfma_f32_16x16x32_bf16 v[76:79], v[144:147], v[212:215], v[76:79]
	v_mfma_f32_16x16x32_bf16 v[68:71], v[152:155], v[212:215], v[68:71]
	v_mfma_f32_16x16x32_bf16 v[124:127], v[148:151], v[180:183], v[124:127]
	v_mfma_f32_16x16x32_bf16 v[116:119], v[156:159], v[180:183], v[116:119]
	v_mfma_f32_16x16x32_bf16 v[108:111], v[148:151], v[188:191], v[108:111]
	v_mfma_f32_16x16x32_bf16 v[100:103], v[156:159], v[188:191], v[100:103]
	v_mfma_f32_16x16x32_bf16 v[92:95], v[148:151], v[208:211], v[92:95]
	v_mfma_f32_16x16x32_bf16 v[84:87], v[156:159], v[208:211], v[84:87]
	v_mfma_f32_16x16x32_bf16 v[76:79], v[148:151], v[216:219], v[76:79]
	v_mfma_f32_16x16x32_bf16 v[68:71], v[156:159], v[216:219], v[68:71]
	s_setprio 0
	s_barrier
	s_add_i32 s24, 0, 0x1c000
	s_add_i32 s25, s44, s28
	v_add_u32_e32 v196, s24, v141
	v_lshl_add_u64 v[160:161], v[160:161], 0, s[6:7]
	s_mov_b32 m0, s25
	ds_read_b128 v[220:223], v196
	ds_read_b128 v[224:227], v196 offset:1024
	ds_read_b128 v[228:231], v196 offset:2048
	ds_read_b128 v[232:235], v196 offset:3072
	global_load_lds_dwordx4 v[160:161], off
	v_lshl_add_u64 v[160:161], v[236:237], 0, s[6:7]
	s_add_i32 m0, s25, 0x2000
	s_nop 0
	global_load_lds_dwordx4 v[160:161], off
	s_barrier
	s_waitcnt lgkmcnt(0)
	s_setprio 1
	s_waitcnt lgkmcnt(0)
	v_mfma_f32_16x16x32_bf16 v[120:123], v[220:223], v[176:179], v[120:123]
	v_mfma_f32_16x16x32_bf16 v[112:115], v[228:231], v[176:179], v[112:115]
	v_mfma_f32_16x16x32_bf16 v[104:107], v[220:223], v[184:187], v[104:107]
	v_mfma_f32_16x16x32_bf16 v[96:99], v[228:231], v[184:187], v[96:99]
	v_mfma_f32_16x16x32_bf16 v[88:91], v[220:223], v[192:195], v[88:91]
	v_mfma_f32_16x16x32_bf16 v[80:83], v[228:231], v[192:195], v[80:83]
	v_mfma_f32_16x16x32_bf16 v[72:75], v[220:223], v[212:215], v[72:75]
	v_mfma_f32_16x16x32_bf16 v[64:67], v[228:231], v[212:215], v[64:67]
	v_mfma_f32_16x16x32_bf16 v[120:123], v[224:227], v[180:183], v[120:123]
	v_mfma_f32_16x16x32_bf16 v[112:115], v[232:235], v[180:183], v[112:115]
	v_mfma_f32_16x16x32_bf16 v[104:107], v[224:227], v[188:191], v[104:107]
	v_mfma_f32_16x16x32_bf16 v[96:99], v[232:235], v[188:191], v[96:99]
	v_mfma_f32_16x16x32_bf16 v[88:91], v[224:227], v[208:211], v[88:91]
	v_mfma_f32_16x16x32_bf16 v[80:83], v[232:235], v[208:211], v[80:83]
	v_mfma_f32_16x16x32_bf16 v[72:75], v[224:227], v[216:219], v[72:75]
	v_mfma_f32_16x16x32_bf16 v[64:67], v[232:235], v[216:219], v[64:67]
	s_setprio 0
	s_mov_b32 m0, s35
	v_lshl_add_u64 v[160:161], v[238:239], 0, s[6:7]
	s_barrier
	ds_read_b128 v[176:179], v143 offset:49152
	ds_read_b128 v[180:183], v143 offset:50176
	ds_read_b128 v[184:187], v143 offset:51200
	ds_read_b128 v[188:191], v143 offset:52224
	ds_read_b128 v[192:195], v143 offset:53248
	ds_read_b128 v[208:211], v143 offset:54272
	ds_read_b128 v[212:215], v143 offset:55296
	ds_read_b128 v[216:219], v143 offset:56320
	global_load_lds_dwordx4 v[160:161], off
	v_lshl_add_u64 v[160:161], v[240:241], 0, s[6:7]
	s_mov_b32 m0, s36
	s_nop 0
	global_load_lds_dwordx4 v[160:161], off
	s_barrier
	s_waitcnt lgkmcnt(0)
	s_setprio 1
	s_waitcnt lgkmcnt(0)
	v_mfma_f32_16x16x32_bf16 v[60:63], v[144:147], v[176:179], v[60:63]
	v_mfma_f32_16x16x32_bf16 v[52:55], v[152:155], v[176:179], v[52:55]
	v_mfma_f32_16x16x32_bf16 v[44:47], v[144:147], v[184:187], v[44:47]
	v_mfma_f32_16x16x32_bf16 v[36:39], v[152:155], v[184:187], v[36:39]
	v_mfma_f32_16x16x32_bf16 v[28:31], v[144:147], v[192:195], v[28:31]
	v_mfma_f32_16x16x32_bf16 v[20:23], v[152:155], v[192:195], v[20:23]
	v_mfma_f32_16x16x32_bf16 v[12:15], v[144:147], v[212:215], v[12:15]
	v_mfma_f32_16x16x32_bf16 v[4:7], v[152:155], v[212:215], v[4:7]
	v_mfma_f32_16x16x32_bf16 v[60:63], v[148:151], v[180:183], v[60:63]
	v_mfma_f32_16x16x32_bf16 v[52:55], v[156:159], v[180:183], v[52:55]
	v_mfma_f32_16x16x32_bf16 v[44:47], v[148:151], v[188:191], v[44:47]
	v_mfma_f32_16x16x32_bf16 v[36:39], v[156:159], v[188:191], v[36:39]
	v_mfma_f32_16x16x32_bf16 v[28:31], v[148:151], v[208:211], v[28:31]
	v_mfma_f32_16x16x32_bf16 v[20:23], v[156:159], v[208:211], v[20:23]
	v_mfma_f32_16x16x32_bf16 v[12:15], v[148:151], v[216:219], v[12:15]
	v_mfma_f32_16x16x32_bf16 v[4:7], v[156:159], v[216:219], v[4:7]
	s_setprio 0
	s_barrier
	s_add_u32 s22, s22, 0x80080
	s_addc_u32 s23, s23, 0
	s_add_i32 s24, s24, s28
	v_lshl_add_u64 v[144:145], s[22:23], 0, v[128:129]
	s_mov_b32 m0, s24
	s_nop 0
	global_load_lds_dwordx4 v[144:145], off
	v_lshl_add_u64 v[144:145], s[22:23], 0, v[130:131]
	s_add_i32 m0, s24, 0x2000
	s_nop 0
	global_load_lds_dwordx4 v[144:145], off
	s_waitcnt vmcnt(6)
	s_barrier
	s_setprio 1
	v_mfma_f32_16x16x32_bf16 v[56:59], v[220:223], v[176:179], v[56:59]
	v_mfma_f32_16x16x32_bf16 v[48:51], v[228:231], v[176:179], v[48:51]
	v_mfma_f32_16x16x32_bf16 v[40:43], v[220:223], v[184:187], v[40:43]
	v_mfma_f32_16x16x32_bf16 v[32:35], v[228:231], v[184:187], v[32:35]
	v_mfma_f32_16x16x32_bf16 v[24:27], v[220:223], v[192:195], v[24:27]
	v_mfma_f32_16x16x32_bf16 v[16:19], v[228:231], v[192:195], v[16:19]
	v_mfma_f32_16x16x32_bf16 v[8:11], v[220:223], v[212:215], v[8:11]
	v_mfma_f32_16x16x32_bf16 v[0:3], v[228:231], v[212:215], v[0:3]
	v_mfma_f32_16x16x32_bf16 v[56:59], v[224:227], v[180:183], v[56:59]
	v_mfma_f32_16x16x32_bf16 v[48:51], v[232:235], v[180:183], v[48:51]
	v_mfma_f32_16x16x32_bf16 v[40:43], v[224:227], v[188:191], v[40:43]
	v_mfma_f32_16x16x32_bf16 v[32:35], v[232:235], v[188:191], v[32:35]
	v_mfma_f32_16x16x32_bf16 v[24:27], v[224:227], v[208:211], v[24:27]
	v_mfma_f32_16x16x32_bf16 v[16:19], v[232:235], v[208:211], v[16:19]
	v_mfma_f32_16x16x32_bf16 v[8:11], v[224:227], v[216:219], v[8:11]
	v_mfma_f32_16x16x32_bf16 v[0:3], v[232:235], v[216:219], v[0:3]
	s_setprio 0
	s_add_i32 s43, s43, 2
	s_add_u32 s20, s20, 0x100
	s_addc_u32 s21, s21, 0
	s_add_u32 s41, s41, 0x100
	s_addc_u32 s42, s42, 0
	s_cmp_gt_u32 s43, 29
	s_barrier
	s_cbranch_scc0 .LBB0_143
	v_lshl_or_b32 v146, s38, 7, v142
	v_lshl_add_u32 v144, s18, 8, v140
	s_mov_b32 s38, s10
	s_mov_b32 s18, s12
	s_mov_b64 s[22:23], s[16:17]
	s_mov_b32 s20, 0xbfb8aa3b
	v_mul_lo_u32 v145, v144, s3
	v_lshl_add_u32 v145, v146, 1, v145
	v_pk_mul_f32 v[148:149], v[124:125], s[20:21] op_sel_hi:[1,0]
	v_pk_mul_f32 v[150:151], v[126:127], s[20:21] op_sel_hi:[1,0]
	v_pk_mul_f32 v[152:153], v[116:117], s[20:21] op_sel_hi:[1,0]
	v_pk_mul_f32 v[154:155], v[118:119], s[20:21] op_sel_hi:[1,0]
	v_exp_f32_e32 v148, v148
	v_exp_f32_e32 v149, v149
	v_exp_f32_e32 v150, v150
	v_exp_f32_e32 v151, v151
	v_exp_f32_e32 v152, v152
	v_exp_f32_e32 v153, v153
	v_exp_f32_e32 v154, v154
	v_exp_f32_e32 v155, v155
	v_pk_add_f32 v[148:149], v[148:149], 1.0 op_sel_hi:[1,0]
	v_pk_add_f32 v[150:151], v[150:151], 1.0 op_sel_hi:[1,0]
	v_pk_add_f32 v[152:153], v[152:153], 1.0 op_sel_hi:[1,0]
	v_pk_add_f32 v[154:155], v[154:155], 1.0 op_sel_hi:[1,0]
	v_rcp_f32_e32 v148, v148
	v_rcp_f32_e32 v149, v149
	v_rcp_f32_e32 v150, v150
	v_rcp_f32_e32 v151, v151
	v_rcp_f32_e32 v152, v152
	v_rcp_f32_e32 v153, v153
	v_rcp_f32_e32 v154, v154
	v_rcp_f32_e32 v155, v155
	v_pk_mul_f32 v[124:125], v[124:125], v[148:149]
	v_pk_mul_f32 v[126:127], v[126:127], v[150:151]
	v_pk_mul_f32 v[116:117], v[116:117], v[152:153]
	v_pk_mul_f32 v[118:119], v[118:119], v[154:155]
	v_pk_mul_f32 v[120:121], v[124:125], v[120:121]
	v_pk_mul_f32 v[122:123], v[126:127], v[122:123]
	v_pk_mul_f32 v[112:113], v[116:117], v[112:113]
	v_pk_mul_f32 v[114:115], v[118:119], v[114:115]
	v_cvt_pk_bf16_f32 v156, v120, v121
	v_cvt_pk_bf16_f32 v157, v122, v123
	v_cvt_pk_bf16_f32 v158, v112, v113
	v_cvt_pk_bf16_f32 v159, v114, v115
	global_store_dwordx4 v145, v[156:159], s[48:49] nt
	v_pk_mul_f32 v[148:149], v[108:109], s[20:21] op_sel_hi:[1,0]
	v_pk_mul_f32 v[150:151], v[110:111], s[20:21] op_sel_hi:[1,0]
	v_pk_mul_f32 v[152:153], v[100:101], s[20:21] op_sel_hi:[1,0]
	v_pk_mul_f32 v[154:155], v[102:103], s[20:21] op_sel_hi:[1,0]
	v_exp_f32_e32 v148, v148
	v_exp_f32_e32 v149, v149
	v_exp_f32_e32 v150, v150
	v_exp_f32_e32 v151, v151
	v_exp_f32_e32 v152, v152
	v_exp_f32_e32 v153, v153
	v_exp_f32_e32 v154, v154
	v_exp_f32_e32 v155, v155
	v_pk_add_f32 v[148:149], v[148:149], 1.0 op_sel_hi:[1,0]
	v_pk_add_f32 v[150:151], v[150:151], 1.0 op_sel_hi:[1,0]
	v_pk_add_f32 v[152:153], v[152:153], 1.0 op_sel_hi:[1,0]
	v_pk_add_f32 v[154:155], v[154:155], 1.0 op_sel_hi:[1,0]
	v_rcp_f32_e32 v148, v148
	v_rcp_f32_e32 v149, v149
	v_rcp_f32_e32 v150, v150
	v_rcp_f32_e32 v151, v151
	v_rcp_f32_e32 v152, v152
	v_rcp_f32_e32 v153, v153
	v_rcp_f32_e32 v154, v154
	v_rcp_f32_e32 v155, v155
	v_pk_mul_f32 v[108:109], v[108:109], v[148:149]
	v_pk_mul_f32 v[110:111], v[110:111], v[150:151]
	v_pk_mul_f32 v[100:101], v[100:101], v[152:153]
	v_pk_mul_f32 v[102:103], v[102:103], v[154:155]
	v_pk_mul_f32 v[104:105], v[108:109], v[104:105]
	v_pk_mul_f32 v[106:107], v[110:111], v[106:107]
	v_pk_mul_f32 v[96:97], v[100:101], v[96:97]
	v_pk_mul_f32 v[98:99], v[102:103], v[98:99]
	v_cvt_pk_bf16_f32 v176, v104, v105
	v_cvt_pk_bf16_f32 v177, v106, v107
	v_cvt_pk_bf16_f32 v178, v96, v97
	v_cvt_pk_bf16_f32 v179, v98, v99
	s_mul_i32 s21, s3, 16
	v_add_u32_e32 v147, s21, v145
	global_store_dwordx4 v147, v[176:179], s[48:49] nt
	v_pk_mul_f32 v[148:149], v[92:93], s[20:21] op_sel_hi:[1,0]
	v_pk_mul_f32 v[150:151], v[94:95], s[20:21] op_sel_hi:[1,0]
	v_pk_mul_f32 v[152:153], v[84:85], s[20:21] op_sel_hi:[1,0]
	v_pk_mul_f32 v[154:155], v[86:87], s[20:21] op_sel_hi:[1,0]
	v_exp_f32_e32 v148, v148
	v_exp_f32_e32 v149, v149
	v_exp_f32_e32 v150, v150
	v_exp_f32_e32 v151, v151
	v_exp_f32_e32 v152, v152
	v_exp_f32_e32 v153, v153
	v_exp_f32_e32 v154, v154
	v_exp_f32_e32 v155, v155
	v_pk_add_f32 v[148:149], v[148:149], 1.0 op_sel_hi:[1,0]
	v_pk_add_f32 v[150:151], v[150:151], 1.0 op_sel_hi:[1,0]
	v_pk_add_f32 v[152:153], v[152:153], 1.0 op_sel_hi:[1,0]
	v_pk_add_f32 v[154:155], v[154:155], 1.0 op_sel_hi:[1,0]
	v_rcp_f32_e32 v148, v148
	v_rcp_f32_e32 v149, v149
	v_rcp_f32_e32 v150, v150
	v_rcp_f32_e32 v151, v151
	v_rcp_f32_e32 v152, v152
	v_rcp_f32_e32 v153, v153
	v_rcp_f32_e32 v154, v154
	v_rcp_f32_e32 v155, v155
	v_pk_mul_f32 v[92:93], v[92:93], v[148:149]
	v_pk_mul_f32 v[94:95], v[94:95], v[150:151]
	v_pk_mul_f32 v[84:85], v[84:85], v[152:153]
	v_pk_mul_f32 v[86:87], v[86:87], v[154:155]
	v_pk_mul_f32 v[88:89], v[92:93], v[88:89]
	v_pk_mul_f32 v[90:91], v[94:95], v[90:91]
	v_pk_mul_f32 v[80:81], v[84:85], v[80:81]
	v_pk_mul_f32 v[82:83], v[86:87], v[82:83]
	v_cvt_pk_bf16_f32 v156, v88, v89
	v_cvt_pk_bf16_f32 v157, v90, v91
	v_cvt_pk_bf16_f32 v158, v80, v81
	v_cvt_pk_bf16_f32 v159, v82, v83
	s_mul_i32 s21, s3, 32
	v_add_u32_e32 v147, s21, v145
	global_store_dwordx4 v147, v[156:159], s[48:49] nt
	v_pk_mul_f32 v[148:149], v[76:77], s[20:21] op_sel_hi:[1,0]
	v_pk_mul_f32 v[150:151], v[78:79], s[20:21] op_sel_hi:[1,0]
	v_pk_mul_f32 v[152:153], v[68:69], s[20:21] op_sel_hi:[1,0]
	v_pk_mul_f32 v[154:155], v[70:71], s[20:21] op_sel_hi:[1,0]
	v_exp_f32_e32 v148, v148
	v_exp_f32_e32 v149, v149
	v_exp_f32_e32 v150, v150
	v_exp_f32_e32 v151, v151
	v_exp_f32_e32 v152, v152
	v_exp_f32_e32 v153, v153
	v_exp_f32_e32 v154, v154
	v_exp_f32_e32 v155, v155
	v_pk_add_f32 v[148:149], v[148:149], 1.0 op_sel_hi:[1,0]
	v_pk_add_f32 v[150:151], v[150:151], 1.0 op_sel_hi:[1,0]
	v_pk_add_f32 v[152:153], v[152:153], 1.0 op_sel_hi:[1,0]
	v_pk_add_f32 v[154:155], v[154:155], 1.0 op_sel_hi:[1,0]
	v_rcp_f32_e32 v148, v148
	v_rcp_f32_e32 v149, v149
	v_rcp_f32_e32 v150, v150
	v_rcp_f32_e32 v151, v151
	v_rcp_f32_e32 v152, v152
	v_rcp_f32_e32 v153, v153
	v_rcp_f32_e32 v154, v154
	v_rcp_f32_e32 v155, v155
	v_pk_mul_f32 v[76:77], v[76:77], v[148:149]
	v_pk_mul_f32 v[78:79], v[78:79], v[150:151]
	v_pk_mul_f32 v[68:69], v[68:69], v[152:153]
	v_pk_mul_f32 v[70:71], v[70:71], v[154:155]
	v_pk_mul_f32 v[72:73], v[76:77], v[72:73]
	v_pk_mul_f32 v[74:75], v[78:79], v[74:75]
	v_pk_mul_f32 v[64:65], v[68:69], v[64:65]
	v_pk_mul_f32 v[66:67], v[70:71], v[66:67]
	v_cvt_pk_bf16_f32 v176, v72, v73
	v_cvt_pk_bf16_f32 v177, v74, v75
	v_cvt_pk_bf16_f32 v178, v64, v65
	v_cvt_pk_bf16_f32 v179, v66, v67
	s_mul_i32 s21, s3, 48
	v_add_u32_e32 v147, s21, v145
	global_store_dwordx4 v147, v[176:179], s[48:49] nt
	v_pk_mul_f32 v[148:149], v[60:61], s[20:21] op_sel_hi:[1,0]
	v_pk_mul_f32 v[150:151], v[62:63], s[20:21] op_sel_hi:[1,0]
	v_pk_mul_f32 v[152:153], v[52:53], s[20:21] op_sel_hi:[1,0]
	v_pk_mul_f32 v[154:155], v[54:55], s[20:21] op_sel_hi:[1,0]
	v_exp_f32_e32 v148, v148
	v_exp_f32_e32 v149, v149
	v_exp_f32_e32 v150, v150
	v_exp_f32_e32 v151, v151
	v_exp_f32_e32 v152, v152
	v_exp_f32_e32 v153, v153
	v_exp_f32_e32 v154, v154
	v_exp_f32_e32 v155, v155
	v_pk_add_f32 v[148:149], v[148:149], 1.0 op_sel_hi:[1,0]
	v_pk_add_f32 v[150:151], v[150:151], 1.0 op_sel_hi:[1,0]
	v_pk_add_f32 v[152:153], v[152:153], 1.0 op_sel_hi:[1,0]
	v_pk_add_f32 v[154:155], v[154:155], 1.0 op_sel_hi:[1,0]
	v_rcp_f32_e32 v148, v148
	v_rcp_f32_e32 v149, v149
	v_rcp_f32_e32 v150, v150
	v_rcp_f32_e32 v151, v151
	v_rcp_f32_e32 v152, v152
	v_rcp_f32_e32 v153, v153
	v_rcp_f32_e32 v154, v154
	v_rcp_f32_e32 v155, v155
	v_pk_mul_f32 v[60:61], v[60:61], v[148:149]
	v_pk_mul_f32 v[62:63], v[62:63], v[150:151]
	v_pk_mul_f32 v[52:53], v[52:53], v[152:153]
	v_pk_mul_f32 v[54:55], v[54:55], v[154:155]
	v_pk_mul_f32 v[56:57], v[60:61], v[56:57]
	v_pk_mul_f32 v[58:59], v[62:63], v[58:59]
	v_pk_mul_f32 v[48:49], v[52:53], v[48:49]
	v_pk_mul_f32 v[50:51], v[54:55], v[50:51]
	v_cvt_pk_bf16_f32 v156, v56, v57
	v_cvt_pk_bf16_f32 v157, v58, v59
	v_cvt_pk_bf16_f32 v158, v48, v49
	v_cvt_pk_bf16_f32 v159, v50, v51
	s_mul_i32 s21, s3, 128
	v_add_u32_e32 v147, s21, v145
	global_store_dwordx4 v147, v[156:159], s[48:49] nt
	v_pk_mul_f32 v[148:149], v[44:45], s[20:21] op_sel_hi:[1,0]
	v_pk_mul_f32 v[150:151], v[46:47], s[20:21] op_sel_hi:[1,0]
	v_pk_mul_f32 v[152:153], v[36:37], s[20:21] op_sel_hi:[1,0]
	v_pk_mul_f32 v[154:155], v[38:39], s[20:21] op_sel_hi:[1,0]
	v_exp_f32_e32 v148, v148
	v_exp_f32_e32 v149, v149
	v_exp_f32_e32 v150, v150
	v_exp_f32_e32 v151, v151
	v_exp_f32_e32 v152, v152
	v_exp_f32_e32 v153, v153
	v_exp_f32_e32 v154, v154
	v_exp_f32_e32 v155, v155
	v_pk_add_f32 v[148:149], v[148:149], 1.0 op_sel_hi:[1,0]
	v_pk_add_f32 v[150:151], v[150:151], 1.0 op_sel_hi:[1,0]
	v_pk_add_f32 v[152:153], v[152:153], 1.0 op_sel_hi:[1,0]
	v_pk_add_f32 v[154:155], v[154:155], 1.0 op_sel_hi:[1,0]
	v_rcp_f32_e32 v148, v148
	v_rcp_f32_e32 v149, v149
	v_rcp_f32_e32 v150, v150
	v_rcp_f32_e32 v151, v151
	v_rcp_f32_e32 v152, v152
	v_rcp_f32_e32 v153, v153
	v_rcp_f32_e32 v154, v154
	v_rcp_f32_e32 v155, v155
	v_pk_mul_f32 v[44:45], v[44:45], v[148:149]
	v_pk_mul_f32 v[46:47], v[46:47], v[150:151]
	v_pk_mul_f32 v[36:37], v[36:37], v[152:153]
	v_pk_mul_f32 v[38:39], v[38:39], v[154:155]
	v_pk_mul_f32 v[40:41], v[44:45], v[40:41]
	v_pk_mul_f32 v[42:43], v[46:47], v[42:43]
	v_pk_mul_f32 v[32:33], v[36:37], v[32:33]
	v_pk_mul_f32 v[34:35], v[38:39], v[34:35]
	v_cvt_pk_bf16_f32 v176, v40, v41
	v_cvt_pk_bf16_f32 v177, v42, v43
	v_cvt_pk_bf16_f32 v178, v32, v33
	v_cvt_pk_bf16_f32 v179, v34, v35
	s_mul_i32 s21, s3, 144
	v_add_u32_e32 v147, s21, v145
	global_store_dwordx4 v147, v[176:179], s[48:49] nt
	v_pk_mul_f32 v[148:149], v[28:29], s[20:21] op_sel_hi:[1,0]
	v_pk_mul_f32 v[150:151], v[30:31], s[20:21] op_sel_hi:[1,0]
	v_pk_mul_f32 v[152:153], v[20:21], s[20:21] op_sel_hi:[1,0]
	v_pk_mul_f32 v[154:155], v[22:23], s[20:21] op_sel_hi:[1,0]
	v_exp_f32_e32 v148, v148
	v_exp_f32_e32 v149, v149
	v_exp_f32_e32 v150, v150
	v_exp_f32_e32 v151, v151
	v_exp_f32_e32 v152, v152
	v_exp_f32_e32 v153, v153
	v_exp_f32_e32 v154, v154
	v_exp_f32_e32 v155, v155
	v_pk_add_f32 v[148:149], v[148:149], 1.0 op_sel_hi:[1,0]
	v_pk_add_f32 v[150:151], v[150:151], 1.0 op_sel_hi:[1,0]
	v_pk_add_f32 v[152:153], v[152:153], 1.0 op_sel_hi:[1,0]
	v_pk_add_f32 v[154:155], v[154:155], 1.0 op_sel_hi:[1,0]
	v_rcp_f32_e32 v148, v148
	v_rcp_f32_e32 v149, v149
	v_rcp_f32_e32 v150, v150
	v_rcp_f32_e32 v151, v151
	v_rcp_f32_e32 v152, v152
	v_rcp_f32_e32 v153, v153
	v_rcp_f32_e32 v154, v154
	v_rcp_f32_e32 v155, v155
	v_pk_mul_f32 v[28:29], v[28:29], v[148:149]
	v_pk_mul_f32 v[30:31], v[30:31], v[150:151]
	v_pk_mul_f32 v[20:21], v[20:21], v[152:153]
	v_pk_mul_f32 v[22:23], v[22:23], v[154:155]
	v_pk_mul_f32 v[24:25], v[28:29], v[24:25]
	v_pk_mul_f32 v[26:27], v[30:31], v[26:27]
	v_pk_mul_f32 v[16:17], v[20:21], v[16:17]
	v_pk_mul_f32 v[18:19], v[22:23], v[18:19]
	v_cvt_pk_bf16_f32 v156, v24, v25
	v_cvt_pk_bf16_f32 v157, v26, v27
	v_cvt_pk_bf16_f32 v158, v16, v17
	v_cvt_pk_bf16_f32 v159, v18, v19
	s_mul_i32 s21, s3, 160
	v_add_u32_e32 v147, s21, v145
	global_store_dwordx4 v147, v[156:159], s[48:49] nt
	v_pk_mul_f32 v[148:149], v[12:13], s[20:21] op_sel_hi:[1,0]
	v_pk_mul_f32 v[150:151], v[14:15], s[20:21] op_sel_hi:[1,0]
	v_pk_mul_f32 v[152:153], v[4:5], s[20:21] op_sel_hi:[1,0]
	v_pk_mul_f32 v[154:155], v[6:7], s[20:21] op_sel_hi:[1,0]
	v_exp_f32_e32 v148, v148
	v_exp_f32_e32 v149, v149
	v_exp_f32_e32 v150, v150
	v_exp_f32_e32 v151, v151
	v_exp_f32_e32 v152, v152
	v_exp_f32_e32 v153, v153
	v_exp_f32_e32 v154, v154
	v_exp_f32_e32 v155, v155
	v_pk_add_f32 v[148:149], v[148:149], 1.0 op_sel_hi:[1,0]
	v_pk_add_f32 v[150:151], v[150:151], 1.0 op_sel_hi:[1,0]
	v_pk_add_f32 v[152:153], v[152:153], 1.0 op_sel_hi:[1,0]
	v_pk_add_f32 v[154:155], v[154:155], 1.0 op_sel_hi:[1,0]
	v_rcp_f32_e32 v148, v148
	v_rcp_f32_e32 v149, v149
	v_rcp_f32_e32 v150, v150
	v_rcp_f32_e32 v151, v151
	v_rcp_f32_e32 v152, v152
	v_rcp_f32_e32 v153, v153
	v_rcp_f32_e32 v154, v154
	v_rcp_f32_e32 v155, v155
	v_pk_mul_f32 v[12:13], v[12:13], v[148:149]
	v_pk_mul_f32 v[14:15], v[14:15], v[150:151]
	v_pk_mul_f32 v[4:5], v[4:5], v[152:153]
	v_pk_mul_f32 v[6:7], v[6:7], v[154:155]
	v_pk_mul_f32 v[8:9], v[12:13], v[8:9]
	v_pk_mul_f32 v[10:11], v[14:15], v[10:11]
	v_pk_mul_f32 v[0:1], v[4:5], v[0:1]
	v_pk_mul_f32 v[2:3], v[6:7], v[2:3]
	v_cvt_pk_bf16_f32 v176, v8, v9
	v_cvt_pk_bf16_f32 v177, v10, v11
	v_cvt_pk_bf16_f32 v178, v0, v1
	v_cvt_pk_bf16_f32 v179, v2, v3
	s_mul_i32 s21, s3, 176
	v_add_u32_e32 v147, s21, v145
	global_store_dwordx4 v147, v[176:179], s[48:49] nt
	s_mov_b64 s[20:21], s[14:15]
	s_and_b64 vcc, exec, s[8:9]
	s_cbranch_vccz .LBB0_140
	s_waitcnt vmcnt(0)
	s_cmpk_gt_u32 s1, 0xff
	s_cbranch_scc1 .LBB0_147
	s_barrier

.LBB0_637:
	s_add_u32 s22, s20, 0xfff80080
	s_addc_u32 s23, s21, -1
	s_add_i32 s44, 0, 0x10000
	v_add_u32_e32 v156, s44, v141
	ds_read_b128 v[144:147], v156
	ds_read_b128 v[148:151], v156 offset:1024
	ds_read_b128 v[152:155], v156 offset:2048
	ds_read_b128 v[156:159], v156 offset:3072
	s_cmp_eq_u32 s43, 28
	s_cselect_b32 s25, s13, s23
	s_cselect_b32 s24, s39, s22
	s_cselect_b32 s23, s11, s42
	s_cselect_b32 s22, s40, s41
	v_lshl_add_u64 v[160:161], s[20:21], 0, v[136:137]
	s_add_i32 m0, s19, 0xc000
	ds_read_b128 v[176:179], v143
	ds_read_b128 v[180:183], v143 offset:1024
	ds_read_b128 v[184:187], v143 offset:2048
	ds_read_b128 v[188:191], v143 offset:3072
	ds_read_b128 v[192:195], v143 offset:4096
	ds_read_b128 v[208:211], v143 offset:5120
	ds_read_b128 v[212:215], v143 offset:6144
	ds_read_b128 v[216:219], v143 offset:7168
	global_load_lds_dwordx4 v[160:161], off
	v_lshl_add_u64 v[160:161], s[20:21], 0, v[138:139]
	s_add_i32 m0, s19, 0xe000
	s_nop 0
	global_load_lds_dwordx4 v[160:161], off
	s_waitcnt lgkmcnt(8)
	s_barrier
	s_waitcnt lgkmcnt(0)
	s_setprio 1
	s_waitcnt lgkmcnt(0)
	v_mfma_f32_16x16x32_bf16 v[124:127], v[144:147], v[176:179], v[124:127]
	v_mfma_f32_16x16x32_bf16 v[116:119], v[152:155], v[176:179], v[116:119]
	v_mfma_f32_16x16x32_bf16 v[108:111], v[144:147], v[184:187], v[108:111]
	v_mfma_f32_16x16x32_bf16 v[100:103], v[152:155], v[184:187], v[100:103]
	v_mfma_f32_16x16x32_bf16 v[92:95], v[144:147], v[192:195], v[92:95]
	v_mfma_f32_16x16x32_bf16 v[84:87], v[152:155], v[192:195], v[84:87]
	v_mfma_f32_16x16x32_bf16 v[76:79], v[144:147], v[212:215], v[76:79]
	v_mfma_f32_16x16x32_bf16 v[68:71], v[152:155], v[212:215], v[68:71]
	v_mfma_f32_16x16x32_bf16 v[124:127], v[148:151], v[180:183], v[124:127]
	v_mfma_f32_16x16x32_bf16 v[116:119], v[156:159], v[180:183], v[116:119]
	v_mfma_f32_16x16x32_bf16 v[108:111], v[148:151], v[188:191], v[108:111]
	v_mfma_f32_16x16x32_bf16 v[100:103], v[156:159], v[188:191], v[100:103]
	v_mfma_f32_16x16x32_bf16 v[92:95], v[148:151], v[208:211], v[92:95]
	v_mfma_f32_16x16x32_bf16 v[84:87], v[156:159], v[208:211], v[84:87]
	v_mfma_f32_16x16x32_bf16 v[76:79], v[148:151], v[216:219], v[76:79]
	v_mfma_f32_16x16x32_bf16 v[68:71], v[156:159], v[216:219], v[68:71]
	s_setprio 0
	s_barrier
	s_add_i32 s46, 0, 0x14000
	v_add_u32_e32 v160, s46, v141
	s_add_i32 s44, s44, s28
	ds_read_b128 v[220:223], v160
	ds_read_b128 v[224:227], v160 offset:1024
	ds_read_b128 v[228:231], v160 offset:2048
	ds_read_b128 v[232:235], v160 offset:3072
	v_lshl_add_u64 v[160:161], s[22:23], 0, v[128:129]
	s_mov_b32 m0, s44
	v_lshl_add_u64 v[236:237], s[22:23], 0, v[130:131]
	global_load_lds_dwordx4 v[160:161], off
	s_add_i32 m0, s44, 0x2000
	s_nop 0
	global_load_lds_dwordx4 v[236:237], off
	s_barrier
	s_waitcnt lgkmcnt(0)
	s_setprio 1
	s_waitcnt lgkmcnt(0)
	v_mfma_f32_16x16x32_bf16 v[120:123], v[220:223], v[176:179], v[120:123]
	v_mfma_f32_16x16x32_bf16 v[112:115], v[228:231], v[176:179], v[112:115]
	v_mfma_f32_16x16x32_bf16 v[104:107], v[220:223], v[184:187], v[104:107]
	v_mfma_f32_16x16x32_bf16 v[96:99], v[228:231], v[184:187], v[96:99]
	v_mfma_f32_16x16x32_bf16 v[88:91], v[220:223], v[192:195], v[88:91]
	v_mfma_f32_16x16x32_bf16 v[80:83], v[228:231], v[192:195], v[80:83]
	v_mfma_f32_16x16x32_bf16 v[72:75], v[220:223], v[212:215], v[72:75]
	v_mfma_f32_16x16x32_bf16 v[64:67], v[228:231], v[212:215], v[64:67]
	v_mfma_f32_16x16x32_bf16 v[120:123], v[224:227], v[180:183], v[120:123]
	v_mfma_f32_16x16x32_bf16 v[112:115], v[232:235], v[180:183], v[112:115]
	v_mfma_f32_16x16x32_bf16 v[104:107], v[224:227], v[188:191], v[104:107]
	v_mfma_f32_16x16x32_bf16 v[96:99], v[232:235], v[188:191], v[96:99]
	v_mfma_f32_16x16x32_bf16 v[88:91], v[224:227], v[208:211], v[88:91]
	v_mfma_f32_16x16x32_bf16 v[80:83], v[232:235], v[208:211], v[80:83]
	v_mfma_f32_16x16x32_bf16 v[72:75], v[224:227], v[216:219], v[72:75]
	v_mfma_f32_16x16x32_bf16 v[64:67], v[232:235], v[216:219], v[64:67]
	s_setprio 0
	s_mov_b32 m0, s19
	v_lshl_add_u64 v[238:239], s[24:25], 0, v[134:135]
	s_barrier
	ds_read_b128 v[176:179], v143 offset:16384
	ds_read_b128 v[180:183], v143 offset:17408
	ds_read_b128 v[184:187], v143 offset:18432
	ds_read_b128 v[188:191], v143 offset:19456
	ds_read_b128 v[192:195], v143 offset:20480
	ds_read_b128 v[208:211], v143 offset:21504
	ds_read_b128 v[212:215], v143 offset:22528
	ds_read_b128 v[216:219], v143 offset:23552
	global_load_lds_dwordx4 v[238:239], off
	v_lshl_add_u64 v[240:241], s[24:25], 0, v[132:133]
	s_mov_b32 m0, s30
	s_nop 0
	global_load_lds_dwordx4 v[240:241], off
	s_barrier
	s_waitcnt lgkmcnt(0)
	s_setprio 1
	s_waitcnt lgkmcnt(0)
	v_mfma_f32_16x16x32_bf16 v[60:63], v[144:147], v[176:179], v[60:63]
	v_mfma_f32_16x16x32_bf16 v[52:55], v[152:155], v[176:179], v[52:55]
	v_mfma_f32_16x16x32_bf16 v[44:47], v[144:147], v[184:187], v[44:47]
	v_mfma_f32_16x16x32_bf16 v[36:39], v[152:155], v[184:187], v[36:39]
	v_mfma_f32_16x16x32_bf16 v[28:31], v[144:147], v[192:195], v[28:31]
	v_mfma_f32_16x16x32_bf16 v[20:23], v[152:155], v[192:195], v[20:23]
	v_mfma_f32_16x16x32_bf16 v[12:15], v[144:147], v[212:215], v[12:15]
	v_mfma_f32_16x16x32_bf16 v[4:7], v[152:155], v[212:215], v[4:7]
	v_mfma_f32_16x16x32_bf16 v[60:63], v[148:151], v[180:183], v[60:63]
	v_mfma_f32_16x16x32_bf16 v[52:55], v[156:159], v[180:183], v[52:55]
	v_mfma_f32_16x16x32_bf16 v[44:47], v[148:151], v[188:191], v[44:47]
	v_mfma_f32_16x16x32_bf16 v[36:39], v[156:159], v[188:191], v[36:39]
	v_mfma_f32_16x16x32_bf16 v[28:31], v[148:151], v[208:211], v[28:31]
	v_mfma_f32_16x16x32_bf16 v[20:23], v[156:159], v[208:211], v[20:23]
	v_mfma_f32_16x16x32_bf16 v[12:15], v[148:151], v[216:219], v[12:15]
	v_mfma_f32_16x16x32_bf16 v[4:7], v[156:159], v[216:219], v[4:7]
	s_setprio 0
	s_barrier
	s_add_u32 s44, s22, 0x80000
	s_addc_u32 s45, s23, 0
	s_add_i32 s46, s46, s28
	v_lshl_add_u64 v[144:145], s[44:45], 0, v[128:129]
	s_mov_b32 m0, s46
	s_nop 0
	global_load_lds_dwordx4 v[144:145], off
	v_lshl_add_u64 v[144:145], s[44:45], 0, v[130:131]
	s_add_i32 m0, s46, 0x2000
	s_nop 0
	global_load_lds_dwordx4 v[144:145], off
	s_waitcnt vmcnt(6)
	s_barrier
	s_setprio 1
	v_mfma_f32_16x16x32_bf16 v[56:59], v[220:223], v[176:179], v[56:59]
	v_mfma_f32_16x16x32_bf16 v[48:51], v[228:231], v[176:179], v[48:51]
	v_mfma_f32_16x16x32_bf16 v[40:43], v[220:223], v[184:187], v[40:43]
	v_mfma_f32_16x16x32_bf16 v[32:35], v[228:231], v[184:187], v[32:35]
	v_mfma_f32_16x16x32_bf16 v[24:27], v[220:223], v[192:195], v[24:27]
	v_mfma_f32_16x16x32_bf16 v[16:19], v[228:231], v[192:195], v[16:19]
	v_mfma_f32_16x16x32_bf16 v[8:11], v[220:223], v[212:215], v[8:11]
	v_mfma_f32_16x16x32_bf16 v[0:3], v[228:231], v[212:215], v[0:3]
	v_mfma_f32_16x16x32_bf16 v[56:59], v[224:227], v[180:183], v[56:59]
	v_mfma_f32_16x16x32_bf16 v[48:51], v[232:235], v[180:183], v[48:51]
	v_mfma_f32_16x16x32_bf16 v[40:43], v[224:227], v[188:191], v[40:43]
	v_mfma_f32_16x16x32_bf16 v[32:35], v[232:235], v[188:191], v[32:35]
	v_mfma_f32_16x16x32_bf16 v[24:27], v[224:227], v[208:211], v[24:27]
	v_mfma_f32_16x16x32_bf16 v[16:19], v[232:235], v[208:211], v[16:19]
	v_mfma_f32_16x16x32_bf16 v[8:11], v[224:227], v[216:219], v[8:11]
	v_mfma_f32_16x16x32_bf16 v[0:3], v[232:235], v[216:219], v[0:3]
	s_setprio 0
	s_add_i32 s44, 0, 0x18000
	v_add_u32_e32 v156, s44, v141
	s_barrier
	ds_read_b128 v[144:147], v156
	ds_read_b128 v[148:151], v156 offset:1024
	ds_read_b128 v[152:155], v156 offset:2048
	ds_read_b128 v[156:159], v156 offset:3072
	s_add_u32 s24, s24, 0x80000
	s_addc_u32 s25, s25, 0
	s_mov_b32 m0, s31
	v_lshl_add_u64 v[220:221], s[24:25], 0, v[134:135]
	ds_read_b128 v[176:179], v143 offset:32768
	ds_read_b128 v[180:183], v143 offset:33792
	ds_read_b128 v[184:187], v143 offset:34816
	ds_read_b128 v[188:191], v143 offset:35840
	ds_read_b128 v[192:195], v143 offset:36864
	ds_read_b128 v[208:211], v143 offset:37888
	ds_read_b128 v[212:215], v143 offset:38912
	ds_read_b128 v[216:219], v143 offset:39936
	global_load_lds_dwordx4 v[220:221], off
	v_lshl_add_u64 v[220:221], s[24:25], 0, v[132:133]
	s_mov_b32 m0, s34
	s_nop 0
	global_load_lds_dwordx4 v[220:221], off
	s_waitcnt lgkmcnt(8)
	s_barrier
	s_waitcnt lgkmcnt(0)
	s_setprio 1
	s_waitcnt lgkmcnt(0)
	v_mfma_f32_16x16x32_bf16 v[124:127], v[144:147], v[176:179], v[124:127]
	v_mfma_f32_16x16x32_bf16 v[116:119], v[152:155], v[176:179], v[116:119]
	v_mfma_f32_16x16x32_bf16 v[108:111], v[144:147], v[184:187], v[108:111]
	v_mfma_f32_16x16x32_bf16 v[100:103], v[152:155], v[184:187], v[100:103]
	v_mfma_f32_16x16x32_bf16 v[92:95], v[144:147], v[192:195], v[92:95]
	v_mfma_f32_16x16x32_bf16 v[84:87], v[152:155], v[192:195], v[84:87]
	v_mfma_f32_16x16x32_bf16 v[76:79], v[144:147], v[212:215], v[76:79]
	v_mfma_f32_16x16x32_bf16 v[68:71], v[152:155], v[212:215], v[68:71]
	v_mfma_f32_16x16x32_bf16 v[124:127], v[148:151], v[180:183], v[124:127]
	v_mfma_f32_16x16x32_bf16 v[116:119], v[156:159], v[180:183], v[116:119]
	v_mfma_f32_16x16x32_bf16 v[108:111], v[148:151], v[188:191], v[108:111]
	v_mfma_f32_16x16x32_bf16 v[100:103], v[156:159], v[188:191], v[100:103]
	v_mfma_f32_16x16x32_bf16 v[92:95], v[148:151], v[208:211], v[92:95]
	v_mfma_f32_16x16x32_bf16 v[84:87], v[156:159], v[208:211], v[84:87]
	v_mfma_f32_16x16x32_bf16 v[76:79], v[148:151], v[216:219], v[76:79]
	v_mfma_f32_16x16x32_bf16 v[68:71], v[156:159], v[216:219], v[68:71]
	s_setprio 0
	s_barrier
	s_add_i32 s24, 0, 0x1c000
	s_add_i32 s25, s44, s28
	v_add_u32_e32 v232, s24, v141
	v_lshl_add_u64 v[160:161], v[160:161], 0, s[6:7]
	s_mov_b32 m0, s25
	ds_read_b128 v[220:223], v232
	ds_read_b128 v[224:227], v232 offset:1024
	ds_read_b128 v[228:231], v232 offset:2048
	ds_read_b128 v[232:235], v232 offset:3072
	global_load_lds_dwordx4 v[160:161], off
	v_lshl_add_u64 v[160:161], v[236:237], 0, s[6:7]
	s_add_i32 m0, s25, 0x2000
	s_nop 0
	global_load_lds_dwordx4 v[160:161], off
	s_barrier
	s_waitcnt lgkmcnt(0)
	s_setprio 1
	s_waitcnt lgkmcnt(0)
	v_mfma_f32_16x16x32_bf16 v[120:123], v[220:223], v[176:179], v[120:123]
	v_mfma_f32_16x16x32_bf16 v[112:115], v[228:231], v[176:179], v[112:115]
	v_mfma_f32_16x16x32_bf16 v[104:107], v[220:223], v[184:187], v[104:107]
	v_mfma_f32_16x16x32_bf16 v[96:99], v[228:231], v[184:187], v[96:99]
	v_mfma_f32_16x16x32_bf16 v[88:91], v[220:223], v[192:195], v[88:91]
	v_mfma_f32_16x16x32_bf16 v[80:83], v[228:231], v[192:195], v[80:83]
	v_mfma_f32_16x16x32_bf16 v[72:75], v[220:223], v[212:215], v[72:75]
	v_mfma_f32_16x16x32_bf16 v[64:67], v[228:231], v[212:215], v[64:67]
	v_mfma_f32_16x16x32_bf16 v[120:123], v[224:227], v[180:183], v[120:123]
	v_mfma_f32_16x16x32_bf16 v[112:115], v[232:235], v[180:183], v[112:115]
	v_mfma_f32_16x16x32_bf16 v[104:107], v[224:227], v[188:191], v[104:107]
	v_mfma_f32_16x16x32_bf16 v[96:99], v[232:235], v[188:191], v[96:99]
	v_mfma_f32_16x16x32_bf16 v[88:91], v[224:227], v[208:211], v[88:91]
	v_mfma_f32_16x16x32_bf16 v[80:83], v[232:235], v[208:211], v[80:83]
	v_mfma_f32_16x16x32_bf16 v[72:75], v[224:227], v[216:219], v[72:75]
	v_mfma_f32_16x16x32_bf16 v[64:67], v[232:235], v[216:219], v[64:67]
	s_setprio 0
	s_mov_b32 m0, s35
	v_lshl_add_u64 v[160:161], v[238:239], 0, s[6:7]
	s_barrier
	ds_read_b128 v[176:179], v143 offset:49152
	ds_read_b128 v[180:183], v143 offset:50176
	ds_read_b128 v[184:187], v143 offset:51200
	ds_read_b128 v[188:191], v143 offset:52224
	ds_read_b128 v[192:195], v143 offset:53248
	ds_read_b128 v[208:211], v143 offset:54272
	ds_read_b128 v[212:215], v143 offset:55296
	ds_read_b128 v[216:219], v143 offset:56320
	global_load_lds_dwordx4 v[160:161], off
	v_lshl_add_u64 v[160:161], v[240:241], 0, s[6:7]
	s_mov_b32 m0, s36
	s_nop 0
	global_load_lds_dwordx4 v[160:161], off
	s_barrier
	s_waitcnt lgkmcnt(0)
	s_setprio 1
	s_waitcnt lgkmcnt(0)
	v_mfma_f32_16x16x32_bf16 v[60:63], v[144:147], v[176:179], v[60:63]
	v_mfma_f32_16x16x32_bf16 v[52:55], v[152:155], v[176:179], v[52:55]
	v_mfma_f32_16x16x32_bf16 v[44:47], v[144:147], v[184:187], v[44:47]
	v_mfma_f32_16x16x32_bf16 v[36:39], v[152:155], v[184:187], v[36:39]
	v_mfma_f32_16x16x32_bf16 v[28:31], v[144:147], v[192:195], v[28:31]
	v_mfma_f32_16x16x32_bf16 v[20:23], v[152:155], v[192:195], v[20:23]
	v_mfma_f32_16x16x32_bf16 v[12:15], v[144:147], v[212:215], v[12:15]
	v_mfma_f32_16x16x32_bf16 v[4:7], v[152:155], v[212:215], v[4:7]
	v_mfma_f32_16x16x32_bf16 v[60:63], v[148:151], v[180:183], v[60:63]
	v_mfma_f32_16x16x32_bf16 v[52:55], v[156:159], v[180:183], v[52:55]
	v_mfma_f32_16x16x32_bf16 v[44:47], v[148:151], v[188:191], v[44:47]
	v_mfma_f32_16x16x32_bf16 v[36:39], v[156:159], v[188:191], v[36:39]
	v_mfma_f32_16x16x32_bf16 v[28:31], v[148:151], v[208:211], v[28:31]
	v_mfma_f32_16x16x32_bf16 v[20:23], v[156:159], v[208:211], v[20:23]
	v_mfma_f32_16x16x32_bf16 v[12:15], v[148:151], v[216:219], v[12:15]
	v_mfma_f32_16x16x32_bf16 v[4:7], v[156:159], v[216:219], v[4:7]
	s_setprio 0
	s_barrier
	s_add_u32 s22, s22, 0x80080
	s_addc_u32 s23, s23, 0
	s_add_i32 s24, s24, s28
	v_lshl_add_u64 v[144:145], s[22:23], 0, v[128:129]
	s_mov_b32 m0, s24
	s_nop 0
	global_load_lds_dwordx4 v[144:145], off
	v_lshl_add_u64 v[144:145], s[22:23], 0, v[130:131]
	s_add_i32 m0, s24, 0x2000
	s_nop 0
	global_load_lds_dwordx4 v[144:145], off
	s_waitcnt vmcnt(6)
	s_barrier
	s_setprio 1
	v_mfma_f32_16x16x32_bf16 v[56:59], v[220:223], v[176:179], v[56:59]
	v_mfma_f32_16x16x32_bf16 v[48:51], v[228:231], v[176:179], v[48:51]
	v_mfma_f32_16x16x32_bf16 v[40:43], v[220:223], v[184:187], v[40:43]
	v_mfma_f32_16x16x32_bf16 v[32:35], v[228:231], v[184:187], v[32:35]
	v_mfma_f32_16x16x32_bf16 v[24:27], v[220:223], v[192:195], v[24:27]
	v_mfma_f32_16x16x32_bf16 v[16:19], v[228:231], v[192:195], v[16:19]
	v_mfma_f32_16x16x32_bf16 v[8:11], v[220:223], v[212:215], v[8:11]
	v_mfma_f32_16x16x32_bf16 v[0:3], v[228:231], v[212:215], v[0:3]
	v_mfma_f32_16x16x32_bf16 v[56:59], v[224:227], v[180:183], v[56:59]
	v_mfma_f32_16x16x32_bf16 v[48:51], v[232:235], v[180:183], v[48:51]
	v_mfma_f32_16x16x32_bf16 v[40:43], v[224:227], v[188:191], v[40:43]
	v_mfma_f32_16x16x32_bf16 v[32:35], v[232:235], v[188:191], v[32:35]
	v_mfma_f32_16x16x32_bf16 v[24:27], v[224:227], v[208:211], v[24:27]
	v_mfma_f32_16x16x32_bf16 v[16:19], v[232:235], v[208:211], v[16:19]
	v_mfma_f32_16x16x32_bf16 v[8:11], v[224:227], v[216:219], v[8:11]
	v_mfma_f32_16x16x32_bf16 v[0:3], v[232:235], v[216:219], v[0:3]
	s_setprio 0
	s_add_i32 s43, s43, 2
	s_add_u32 s20, s20, 0x100
	s_addc_u32 s21, s21, 0
	s_add_u32 s41, s41, 0x100
	s_addc_u32 s42, s42, 0
	s_cmp_gt_u32 s43, 29
	s_barrier
	s_cbranch_scc0 .LBB0_637
	v_lshl_or_b32 v146, s38, 7, v142
	v_lshl_add_u32 v144, s18, 8, v140
	s_mov_b32 s38, s10
	s_mov_b32 s18, s12
	s_mov_b64 s[22:23], s[16:17]
	s_mov_b32 s20, 0xbfb8aa3b
	v_mul_lo_u32 v145, v144, s3
	v_lshl_add_u32 v145, v146, 1, v145
	v_pk_mul_f32 v[148:149], v[124:125], s[20:21] op_sel_hi:[1,0]
	v_pk_mul_f32 v[150:151], v[126:127], s[20:21] op_sel_hi:[1,0]
	v_pk_mul_f32 v[152:153], v[116:117], s[20:21] op_sel_hi:[1,0]
	v_pk_mul_f32 v[154:155], v[118:119], s[20:21] op_sel_hi:[1,0]
	v_exp_f32_e32 v148, v148
	v_exp_f32_e32 v149, v149
	v_exp_f32_e32 v150, v150
	v_exp_f32_e32 v151, v151
	v_exp_f32_e32 v152, v152
	v_exp_f32_e32 v153, v153
	v_exp_f32_e32 v154, v154
	v_exp_f32_e32 v155, v155
	v_pk_add_f32 v[148:149], v[148:149], 1.0 op_sel_hi:[1,0]
	v_pk_add_f32 v[150:151], v[150:151], 1.0 op_sel_hi:[1,0]
	v_pk_add_f32 v[152:153], v[152:153], 1.0 op_sel_hi:[1,0]
	v_pk_add_f32 v[154:155], v[154:155], 1.0 op_sel_hi:[1,0]
	v_rcp_f32_e32 v148, v148
	v_rcp_f32_e32 v149, v149
	v_rcp_f32_e32 v150, v150
	v_rcp_f32_e32 v151, v151
	v_rcp_f32_e32 v152, v152
	v_rcp_f32_e32 v153, v153
	v_rcp_f32_e32 v154, v154
	v_rcp_f32_e32 v155, v155
	v_pk_mul_f32 v[124:125], v[124:125], v[148:149]
	v_pk_mul_f32 v[126:127], v[126:127], v[150:151]
	v_pk_mul_f32 v[116:117], v[116:117], v[152:153]
	v_pk_mul_f32 v[118:119], v[118:119], v[154:155]
	v_pk_mul_f32 v[120:121], v[124:125], v[120:121]
	v_pk_mul_f32 v[122:123], v[126:127], v[122:123]
	v_pk_mul_f32 v[112:113], v[116:117], v[112:113]
	v_pk_mul_f32 v[114:115], v[118:119], v[114:115]
	v_cvt_pk_bf16_f32 v156, v120, v121
	v_cvt_pk_bf16_f32 v157, v122, v123
	v_cvt_pk_bf16_f32 v158, v112, v113
	v_cvt_pk_bf16_f32 v159, v114, v115
	global_store_dwordx4 v145, v[156:159], s[48:49] nt
	v_pk_mul_f32 v[148:149], v[108:109], s[20:21] op_sel_hi:[1,0]
	v_pk_mul_f32 v[150:151], v[110:111], s[20:21] op_sel_hi:[1,0]
	v_pk_mul_f32 v[152:153], v[100:101], s[20:21] op_sel_hi:[1,0]
	v_pk_mul_f32 v[154:155], v[102:103], s[20:21] op_sel_hi:[1,0]
	v_exp_f32_e32 v148, v148
	v_exp_f32_e32 v149, v149
	v_exp_f32_e32 v150, v150
	v_exp_f32_e32 v151, v151
	v_exp_f32_e32 v152, v152
	v_exp_f32_e32 v153, v153
	v_exp_f32_e32 v154, v154
	v_exp_f32_e32 v155, v155
	v_pk_add_f32 v[148:149], v[148:149], 1.0 op_sel_hi:[1,0]
	v_pk_add_f32 v[150:151], v[150:151], 1.0 op_sel_hi:[1,0]
	v_pk_add_f32 v[152:153], v[152:153], 1.0 op_sel_hi:[1,0]
	v_pk_add_f32 v[154:155], v[154:155], 1.0 op_sel_hi:[1,0]
	v_rcp_f32_e32 v148, v148
	v_rcp_f32_e32 v149, v149
	v_rcp_f32_e32 v150, v150
	v_rcp_f32_e32 v151, v151
	v_rcp_f32_e32 v152, v152
	v_rcp_f32_e32 v153, v153
	v_rcp_f32_e32 v154, v154
	v_rcp_f32_e32 v155, v155
	v_pk_mul_f32 v[108:109], v[108:109], v[148:149]
	v_pk_mul_f32 v[110:111], v[110:111], v[150:151]
	v_pk_mul_f32 v[100:101], v[100:101], v[152:153]
	v_pk_mul_f32 v[102:103], v[102:103], v[154:155]
	v_pk_mul_f32 v[104:105], v[108:109], v[104:105]
	v_pk_mul_f32 v[106:107], v[110:111], v[106:107]
	v_pk_mul_f32 v[96:97], v[100:101], v[96:97]
	v_pk_mul_f32 v[98:99], v[102:103], v[98:99]
	v_cvt_pk_bf16_f32 v176, v104, v105
	v_cvt_pk_bf16_f32 v177, v106, v107
	v_cvt_pk_bf16_f32 v178, v96, v97
	v_cvt_pk_bf16_f32 v179, v98, v99
	s_mul_i32 s21, s3, 16
	v_add_u32_e32 v147, s21, v145
	global_store_dwordx4 v147, v[176:179], s[48:49] nt
	v_pk_mul_f32 v[148:149], v[92:93], s[20:21] op_sel_hi:[1,0]
	v_pk_mul_f32 v[150:151], v[94:95], s[20:21] op_sel_hi:[1,0]
	v_pk_mul_f32 v[152:153], v[84:85], s[20:21] op_sel_hi:[1,0]
	v_pk_mul_f32 v[154:155], v[86:87], s[20:21] op_sel_hi:[1,0]
	v_exp_f32_e32 v148, v148
	v_exp_f32_e32 v149, v149
	v_exp_f32_e32 v150, v150
	v_exp_f32_e32 v151, v151
	v_exp_f32_e32 v152, v152
	v_exp_f32_e32 v153, v153
	v_exp_f32_e32 v154, v154
	v_exp_f32_e32 v155, v155
	v_pk_add_f32 v[148:149], v[148:149], 1.0 op_sel_hi:[1,0]
	v_pk_add_f32 v[150:151], v[150:151], 1.0 op_sel_hi:[1,0]
	v_pk_add_f32 v[152:153], v[152:153], 1.0 op_sel_hi:[1,0]
	v_pk_add_f32 v[154:155], v[154:155], 1.0 op_sel_hi:[1,0]
	v_rcp_f32_e32 v148, v148
	v_rcp_f32_e32 v149, v149
	v_rcp_f32_e32 v150, v150
	v_rcp_f32_e32 v151, v151
	v_rcp_f32_e32 v152, v152
	v_rcp_f32_e32 v153, v153
	v_rcp_f32_e32 v154, v154
	v_rcp_f32_e32 v155, v155
	v_pk_mul_f32 v[92:93], v[92:93], v[148:149]
	v_pk_mul_f32 v[94:95], v[94:95], v[150:151]
	v_pk_mul_f32 v[84:85], v[84:85], v[152:153]
	v_pk_mul_f32 v[86:87], v[86:87], v[154:155]
	v_pk_mul_f32 v[88:89], v[92:93], v[88:89]
	v_pk_mul_f32 v[90:91], v[94:95], v[90:91]
	v_pk_mul_f32 v[80:81], v[84:85], v[80:81]
	v_pk_mul_f32 v[82:83], v[86:87], v[82:83]
	v_cvt_pk_bf16_f32 v156, v88, v89
	v_cvt_pk_bf16_f32 v157, v90, v91
	v_cvt_pk_bf16_f32 v158, v80, v81
	v_cvt_pk_bf16_f32 v159, v82, v83
	s_mul_i32 s21, s3, 32
	v_add_u32_e32 v147, s21, v145
	global_store_dwordx4 v147, v[156:159], s[48:49] nt
	v_pk_mul_f32 v[148:149], v[76:77], s[20:21] op_sel_hi:[1,0]
	v_pk_mul_f32 v[150:151], v[78:79], s[20:21] op_sel_hi:[1,0]
	v_pk_mul_f32 v[152:153], v[68:69], s[20:21] op_sel_hi:[1,0]
	v_pk_mul_f32 v[154:155], v[70:71], s[20:21] op_sel_hi:[1,0]
	v_exp_f32_e32 v148, v148
	v_exp_f32_e32 v149, v149
	v_exp_f32_e32 v150, v150
	v_exp_f32_e32 v151, v151
	v_exp_f32_e32 v152, v152
	v_exp_f32_e32 v153, v153
	v_exp_f32_e32 v154, v154
	v_exp_f32_e32 v155, v155
	v_pk_add_f32 v[148:149], v[148:149], 1.0 op_sel_hi:[1,0]
	v_pk_add_f32 v[150:151], v[150:151], 1.0 op_sel_hi:[1,0]
	v_pk_add_f32 v[152:153], v[152:153], 1.0 op_sel_hi:[1,0]
	v_pk_add_f32 v[154:155], v[154:155], 1.0 op_sel_hi:[1,0]
	v_rcp_f32_e32 v148, v148
	v_rcp_f32_e32 v149, v149
	v_rcp_f32_e32 v150, v150
	v_rcp_f32_e32 v151, v151
	v_rcp_f32_e32 v152, v152
	v_rcp_f32_e32 v153, v153
	v_rcp_f32_e32 v154, v154
	v_rcp_f32_e32 v155, v155
	v_pk_mul_f32 v[76:77], v[76:77], v[148:149]
	v_pk_mul_f32 v[78:79], v[78:79], v[150:151]
	v_pk_mul_f32 v[68:69], v[68:69], v[152:153]
	v_pk_mul_f32 v[70:71], v[70:71], v[154:155]
	v_pk_mul_f32 v[72:73], v[76:77], v[72:73]
	v_pk_mul_f32 v[74:75], v[78:79], v[74:75]
	v_pk_mul_f32 v[64:65], v[68:69], v[64:65]
	v_pk_mul_f32 v[66:67], v[70:71], v[66:67]
	v_cvt_pk_bf16_f32 v176, v72, v73
	v_cvt_pk_bf16_f32 v177, v74, v75
	v_cvt_pk_bf16_f32 v178, v64, v65
	v_cvt_pk_bf16_f32 v179, v66, v67
	s_mul_i32 s21, s3, 48
	v_add_u32_e32 v147, s21, v145
	global_store_dwordx4 v147, v[176:179], s[48:49] nt
	v_pk_mul_f32 v[148:149], v[60:61], s[20:21] op_sel_hi:[1,0]
	v_pk_mul_f32 v[150:151], v[62:63], s[20:21] op_sel_hi:[1,0]
	v_pk_mul_f32 v[152:153], v[52:53], s[20:21] op_sel_hi:[1,0]
	v_pk_mul_f32 v[154:155], v[54:55], s[20:21] op_sel_hi:[1,0]
	v_exp_f32_e32 v148, v148
	v_exp_f32_e32 v149, v149
	v_exp_f32_e32 v150, v150
	v_exp_f32_e32 v151, v151
	v_exp_f32_e32 v152, v152
	v_exp_f32_e32 v153, v153
	v_exp_f32_e32 v154, v154
	v_exp_f32_e32 v155, v155
	v_pk_add_f32 v[148:149], v[148:149], 1.0 op_sel_hi:[1,0]
	v_pk_add_f32 v[150:151], v[150:151], 1.0 op_sel_hi:[1,0]
	v_pk_add_f32 v[152:153], v[152:153], 1.0 op_sel_hi:[1,0]
	v_pk_add_f32 v[154:155], v[154:155], 1.0 op_sel_hi:[1,0]
	v_rcp_f32_e32 v148, v148
	v_rcp_f32_e32 v149, v149
	v_rcp_f32_e32 v150, v150
	v_rcp_f32_e32 v151, v151
	v_rcp_f32_e32 v152, v152
	v_rcp_f32_e32 v153, v153
	v_rcp_f32_e32 v154, v154
	v_rcp_f32_e32 v155, v155
	v_pk_mul_f32 v[60:61], v[60:61], v[148:149]
	v_pk_mul_f32 v[62:63], v[62:63], v[150:151]
	v_pk_mul_f32 v[52:53], v[52:53], v[152:153]
	v_pk_mul_f32 v[54:55], v[54:55], v[154:155]
	v_pk_mul_f32 v[56:57], v[60:61], v[56:57]
	v_pk_mul_f32 v[58:59], v[62:63], v[58:59]
	v_pk_mul_f32 v[48:49], v[52:53], v[48:49]
	v_pk_mul_f32 v[50:51], v[54:55], v[50:51]
	v_cvt_pk_bf16_f32 v156, v56, v57
	v_cvt_pk_bf16_f32 v157, v58, v59
	v_cvt_pk_bf16_f32 v158, v48, v49
	v_cvt_pk_bf16_f32 v159, v50, v51
	s_mul_i32 s21, s3, 128
	v_add_u32_e32 v147, s21, v145
	global_store_dwordx4 v147, v[156:159], s[48:49] nt
	v_pk_mul_f32 v[148:149], v[44:45], s[20:21] op_sel_hi:[1,0]
	v_pk_mul_f32 v[150:151], v[46:47], s[20:21] op_sel_hi:[1,0]
	v_pk_mul_f32 v[152:153], v[36:37], s[20:21] op_sel_hi:[1,0]
	v_pk_mul_f32 v[154:155], v[38:39], s[20:21] op_sel_hi:[1,0]
	v_exp_f32_e32 v148, v148
	v_exp_f32_e32 v149, v149
	v_exp_f32_e32 v150, v150
	v_exp_f32_e32 v151, v151
	v_exp_f32_e32 v152, v152
	v_exp_f32_e32 v153, v153
	v_exp_f32_e32 v154, v154
	v_exp_f32_e32 v155, v155
	v_pk_add_f32 v[148:149], v[148:149], 1.0 op_sel_hi:[1,0]
	v_pk_add_f32 v[150:151], v[150:151], 1.0 op_sel_hi:[1,0]
	v_pk_add_f32 v[152:153], v[152:153], 1.0 op_sel_hi:[1,0]
	v_pk_add_f32 v[154:155], v[154:155], 1.0 op_sel_hi:[1,0]
	v_rcp_f32_e32 v148, v148
	v_rcp_f32_e32 v149, v149
	v_rcp_f32_e32 v150, v150
	v_rcp_f32_e32 v151, v151
	v_rcp_f32_e32 v152, v152
	v_rcp_f32_e32 v153, v153
	v_rcp_f32_e32 v154, v154
	v_rcp_f32_e32 v155, v155
	v_pk_mul_f32 v[44:45], v[44:45], v[148:149]
	v_pk_mul_f32 v[46:47], v[46:47], v[150:151]
	v_pk_mul_f32 v[36:37], v[36:37], v[152:153]
	v_pk_mul_f32 v[38:39], v[38:39], v[154:155]
	v_pk_mul_f32 v[40:41], v[44:45], v[40:41]
	v_pk_mul_f32 v[42:43], v[46:47], v[42:43]
	v_pk_mul_f32 v[32:33], v[36:37], v[32:33]
	v_pk_mul_f32 v[34:35], v[38:39], v[34:35]
	v_cvt_pk_bf16_f32 v176, v40, v41
	v_cvt_pk_bf16_f32 v177, v42, v43
	v_cvt_pk_bf16_f32 v178, v32, v33
	v_cvt_pk_bf16_f32 v179, v34, v35
	s_mul_i32 s21, s3, 144
	v_add_u32_e32 v147, s21, v145
	global_store_dwordx4 v147, v[176:179], s[48:49] nt
	v_pk_mul_f32 v[148:149], v[28:29], s[20:21] op_sel_hi:[1,0]
	v_pk_mul_f32 v[150:151], v[30:31], s[20:21] op_sel_hi:[1,0]
	v_pk_mul_f32 v[152:153], v[20:21], s[20:21] op_sel_hi:[1,0]
	v_pk_mul_f32 v[154:155], v[22:23], s[20:21] op_sel_hi:[1,0]
	v_exp_f32_e32 v148, v148
	v_exp_f32_e32 v149, v149
	v_exp_f32_e32 v150, v150
	v_exp_f32_e32 v151, v151
	v_exp_f32_e32 v152, v152
	v_exp_f32_e32 v153, v153
	v_exp_f32_e32 v154, v154
	v_exp_f32_e32 v155, v155
	v_pk_add_f32 v[148:149], v[148:149], 1.0 op_sel_hi:[1,0]
	v_pk_add_f32 v[150:151], v[150:151], 1.0 op_sel_hi:[1,0]
	v_pk_add_f32 v[152:153], v[152:153], 1.0 op_sel_hi:[1,0]
	v_pk_add_f32 v[154:155], v[154:155], 1.0 op_sel_hi:[1,0]
	v_rcp_f32_e32 v148, v148
	v_rcp_f32_e32 v149, v149
	v_rcp_f32_e32 v150, v150
	v_rcp_f32_e32 v151, v151
	v_rcp_f32_e32 v152, v152
	v_rcp_f32_e32 v153, v153
	v_rcp_f32_e32 v154, v154
	v_rcp_f32_e32 v155, v155
	v_pk_mul_f32 v[28:29], v[28:29], v[148:149]
	v_pk_mul_f32 v[30:31], v[30:31], v[150:151]
	v_pk_mul_f32 v[20:21], v[20:21], v[152:153]
	v_pk_mul_f32 v[22:23], v[22:23], v[154:155]
	v_pk_mul_f32 v[24:25], v[28:29], v[24:25]
	v_pk_mul_f32 v[26:27], v[30:31], v[26:27]
	v_pk_mul_f32 v[16:17], v[20:21], v[16:17]
	v_pk_mul_f32 v[18:19], v[22:23], v[18:19]
	v_cvt_pk_bf16_f32 v156, v24, v25
	v_cvt_pk_bf16_f32 v157, v26, v27
	v_cvt_pk_bf16_f32 v158, v16, v17
	v_cvt_pk_bf16_f32 v159, v18, v19
	s_mul_i32 s21, s3, 160
	v_add_u32_e32 v147, s21, v145
	global_store_dwordx4 v147, v[156:159], s[48:49] nt
	v_pk_mul_f32 v[148:149], v[12:13], s[20:21] op_sel_hi:[1,0]
	v_pk_mul_f32 v[150:151], v[14:15], s[20:21] op_sel_hi:[1,0]
	v_pk_mul_f32 v[152:153], v[4:5], s[20:21] op_sel_hi:[1,0]
	v_pk_mul_f32 v[154:155], v[6:7], s[20:21] op_sel_hi:[1,0]
	v_exp_f32_e32 v148, v148
	v_exp_f32_e32 v149, v149
	v_exp_f32_e32 v150, v150
	v_exp_f32_e32 v151, v151
	v_exp_f32_e32 v152, v152
	v_exp_f32_e32 v153, v153
	v_exp_f32_e32 v154, v154
	v_exp_f32_e32 v155, v155
	v_pk_add_f32 v[148:149], v[148:149], 1.0 op_sel_hi:[1,0]
	v_pk_add_f32 v[150:151], v[150:151], 1.0 op_sel_hi:[1,0]
	v_pk_add_f32 v[152:153], v[152:153], 1.0 op_sel_hi:[1,0]
	v_pk_add_f32 v[154:155], v[154:155], 1.0 op_sel_hi:[1,0]
	v_rcp_f32_e32 v148, v148
	v_rcp_f32_e32 v149, v149
	v_rcp_f32_e32 v150, v150
	v_rcp_f32_e32 v151, v151
	v_rcp_f32_e32 v152, v152
	v_rcp_f32_e32 v153, v153
	v_rcp_f32_e32 v154, v154
	v_rcp_f32_e32 v155, v155
	v_pk_mul_f32 v[12:13], v[12:13], v[148:149]
	v_pk_mul_f32 v[14:15], v[14:15], v[150:151]
	v_pk_mul_f32 v[4:5], v[4:5], v[152:153]
	v_pk_mul_f32 v[6:7], v[6:7], v[154:155]
	v_pk_mul_f32 v[8:9], v[12:13], v[8:9]
	v_pk_mul_f32 v[10:11], v[14:15], v[10:11]
	v_pk_mul_f32 v[0:1], v[4:5], v[0:1]
	v_pk_mul_f32 v[2:3], v[6:7], v[2:3]
	v_cvt_pk_bf16_f32 v176, v8, v9
	v_cvt_pk_bf16_f32 v177, v10, v11
	v_cvt_pk_bf16_f32 v178, v0, v1
	v_cvt_pk_bf16_f32 v179, v2, v3
	s_mul_i32 s21, s3, 176
	v_add_u32_e32 v147, s21, v145
	global_store_dwordx4 v147, v[176:179], s[48:49] nt
	s_mov_b64 s[20:21], s[14:15]
	s_and_b64 vcc, exec, s[8:9]
	s_cbranch_vccz .LBB0_634
	s_waitcnt vmcnt(0)
	s_cmpk_gt_u32 s1, 0xff
	s_cbranch_scc1 .LBB0_641
	s_barrier
